# static s_setprio 1 for waves 4-7 during the RG-LRU/attention phase (timing only), on top of the stacked version
# speedup vs baseline: 1.0281x; 1.0281x over previous
.LBB0_340:
	s_or_b64 exec, exec, s[2:3]
	v_readlane_b32 s2, v254, 9
	v_mov_b32_e32 v1, v180
	s_mov_b32 s5, s2
	s_waitcnt lgkmcnt(0)
	s_barrier
	v_readfirstlane_b32 s2, v180
	s_nop 3
	s_cmp_ge_u32 s2, 0x100
	s_cbranch_scc0 .Lprio_p3
	s_setprio 1
.Lprio_p3:
	s_and_b32 s2, s5, 7
	v_readlane_b32 s26, v254, 0
	s_cmp_lg_u32 s2, 0
	v_readlane_b32 s3, v254, 10
	s_cbranch_scc1 .LBB0_342
	s_ashr_i32 s3, s26, 31
	s_lshr_b32 s3, s3, 29
	s_add_i32 s3, s26, s3
	s_ashr_i32 s6, s3, 3
	s_and_b32 s3, s3, -8
	s_ashr_i32 s2, s5, 3
	s_sub_i32 s3, s26, s3
	s_mul_i32 s2, s3, s2
	s_add_i32 s26, s2, s6
